# RWKV record builder: next iteration's projection and lora rows touched one iteration ahead (loads whose results are discarded) so the real loads hit L2
# baseline (speedup 1.0000x reference)
.LBB0_326:
	s_bfe_u32 s23, s23, 0x10006
	v_bfe_u32 v0, v107, 3, 3
	v_lshl_or_b32 v109, s23, 3, v0
	s_lshl_b32 s14, s26, 6
	v_lshlrev_b32_e32 v106, 3, v108
	v_cmp_gt_u32_e32 vcc, s7, v109
	s_and_b32 s14, s14, 0x1c0
	v_and_b32_e32 v88, 56, v106
	v_cndmask_b32_e32 v0, 0, v109, vcc
	v_or_b32_e32 v14, s14, v88
	v_add_u32_e32 v6, s25, v0
	v_or_b32_e32 v8, s24, v0
	s_waitcnt lgkmcnt(0)
	v_mov_b64_e32 v[0:1], s[4:5]
	v_mad_i64_i32 v[0:1], s[4:5], v6, s83, v[0:1]
	v_lshlrev_b32_e32 v156, 1, v14
	v_lshl_add_u64 v[0:1], v[0:1], 0, v[156:157]
	s_mov_b64 s[4:5], 0x12f01000
	v_lshl_add_u64 v[2:3], v[0:1], 0, s[4:5]
	v_mov_b64_e32 v[4:5], s[2:3]
	s_movk_i32 s2, 0xc00
	s_mov_b32 s4, 0x12f01000
	v_mad_i64_i32 v[4:5], s[2:3], v6, s2, v[4:5]
	v_add_co_u32_e32 v0, vcc, s4, v0
	v_lshl_add_u64 v[4:5], v[4:5], 0, v[156:157]
	s_mov_b64 s[2:3], 0x25600000
	v_addc_co_u32_e32 v1, vcc, 0, v1, vcc
	s_mov_b32 s4, 0x25600000
	v_lshl_add_u64 v[6:7], v[4:5], 0, s[2:3]
	v_cmp_eq_u32_e64 s[2:3], 0, v8
	v_add_co_u32_e32 v4, vcc, s4, v4
	s_nop 0
	v_cndmask_b32_e64 v9, -1, 0, s[2:3]
	v_cndmask_b32_e64 v8, v205, 0, s[2:3]
	v_addc_co_u32_e32 v5, vcc, 0, v5, vcc
	v_lshl_add_u64 v[12:13], v[2:3], 0, v[8:9]
	s_cmpk_lt_i32 s6, 0x1c00
	s_cbranch_scc0 .Lr1_nopf
	s_mov_b32 s100, 0xf00000
	s_mov_b32 s101, 0
	v_lshl_add_u64 v[160:161], v[2:3], 0, s[100:101]
	v_lshl_add_u64 v[162:163], v[12:13], 0, s[100:101]
	s_mov_b32 s100, 0x600000
	v_lshl_add_u64 v[164:165], v[6:7], 0, s[100:101]
.Lr1_nopf:
	global_load_dwordx4 v[8:11], v[4:5], off
	global_load_dwordx4 v[76:79], v[12:13], off
	global_load_dwordx4 v[32:35], v[12:13], off offset:1024
	global_load_dwordx4 v[36:39], v[2:3], off offset:1024
	global_load_dwordx4 v[24:27], v[2:3], off offset:2048
	s_load_dwordx2 s[4:5], s[18:19], 0xb0
	v_lshlrev_b32_e32 v156, 2, v14
	global_load_dwordx4 v[80:83], v[0:1], off
	global_load_dwordx4 v[28:31], v[12:13], off offset:2048
	global_load_dwordx4 v[72:75], v[6:7], off offset:1024
	s_nop 0
	global_load_dwordx4 v[0:3], v[6:7], off offset:2048
	s_cmpk_lt_i32 s6, 0x1c00
	s_cbranch_scc0 .Lr1_nopf2
	global_load_dwordx4 v[170:173], v[160:161], off
	global_load_dwordx4 v[170:173], v[160:161], off offset:1024
	global_load_dwordx4 v[170:173], v[160:161], off offset:2048
	global_load_dwordx4 v[170:173], v[162:163], off
	global_load_dwordx4 v[170:173], v[162:163], off offset:1024
	global_load_dwordx4 v[170:173], v[162:163], off offset:2048
	global_load_dwordx4 v[170:173], v[164:165], off
	global_load_dwordx4 v[170:173], v[164:165], off offset:1024
	global_load_dwordx4 v[170:173], v[164:165], off offset:2048
.Lr1_nopf2:
	s_waitcnt lgkmcnt(0)
	global_load_dwordx4 v[52:55], v156, s[4:5] offset:16
	global_load_dwordx4 v[56:59], v156, s[4:5]
	global_load_dwordx4 v[40:43], v156, s[4:5] offset:2064
	global_load_dwordx4 v[48:51], v156, s[4:5] offset:2048
	v_lshl_add_u64 v[4:5], s[4:5], 0, v[156:157]
	v_lshl_add_u64 v[6:7], v[4:5], 0, s[46:47]
	v_add_co_u32_e32 v4, vcc, 0x1000, v4
	v_cmp_le_u32_e64 s[4:5], s7, v109
	s_nop 0
	v_addc_co_u32_e32 v5, vcc, 0, v5, vcc
	global_load_dwordx4 v[12:15], v[4:5], off
	s_nop 0
	global_load_dwordx4 v[4:7], v[6:7], off offset:16
	s_and_b64 s[14:15], s[12:13], s[2:3]
	v_mov_b32_e32 v60, 0
	v_mov_b32_e32 v61, 0
	v_mov_b32_e32 v62, 0
	v_mov_b32_e32 v63, 0
	v_mov_b32_e32 v64, 0
	v_mov_b32_e32 v65, 0
	v_mov_b32_e32 v66, 0
	v_mov_b32_e32 v67, 0
	v_mov_b32_e32 v68, 0
	v_mov_b32_e32 v69, 0
	v_mov_b32_e32 v70, 0
	v_mov_b32_e32 v71, 0
	v_mov_b32_e32 v44, 0
	v_mov_b32_e32 v45, 0
	v_mov_b32_e32 v46, 0
	v_mov_b32_e32 v47, 0
	v_mov_b32_e32 v20, 0
	v_mov_b32_e32 v21, 0
	v_mov_b32_e32 v22, 0
	v_mov_b32_e32 v23, 0
	v_mov_b32_e32 v16, 0
	v_mov_b32_e32 v17, 0
	v_mov_b32_e32 v18, 0
	v_mov_b32_e32 v19, 0
	s_and_saveexec_b64 s[12:13], s[14:15]
	s_cbranch_execz .LBB0_328
	s_load_dwordx2 s[14:15], s[18:19], 0x30
	s_mul_hi_i32 s7, s1, 0x1c00
	s_mulk_i32 s1, 0x1c00
	s_waitcnt lgkmcnt(0)
	s_add_u32 s14, s14, s1
	s_addc_u32 s15, s15, s7
	v_lshl_add_u64 v[16:17], s[14:15], 0, v[156:157]
	global_load_dwordx4 v[60:63], v156, s[14:15]
	global_load_dwordx4 v[64:67], v156, s[14:15] offset:16
	global_load_dwordx4 v[68:71], v156, s[14:15] offset:2048
	global_load_dwordx4 v[44:47], v156, s[14:15] offset:2064
	v_lshl_add_u64 v[18:19], v[16:17], 0, s[46:47]
	v_add_co_u32_e32 v16, vcc, 0x1000, v16
	s_nop 1
	v_addc_co_u32_e32 v17, vcc, 0, v17, vcc
	global_load_dwordx4 v[20:23], v[16:17], off
	s_nop 0
	global_load_dwordx4 v[16:19], v[18:19], off offset:16

	.amdhsa_kernel _Z10hybrid_fwd4Args
		.amdhsa_group_segment_fixed_size 0
		.amdhsa_private_segment_fixed_size 0
		.amdhsa_kernarg_size 608
		.amdhsa_user_sgpr_count 2
		.amdhsa_user_sgpr_dispatch_ptr 0
		.amdhsa_user_sgpr_queue_ptr 0
		.amdhsa_user_sgpr_kernarg_segment_ptr 1
		.amdhsa_user_sgpr_dispatch_id 0
		.amdhsa_user_sgpr_kernarg_preload_length 0
		.amdhsa_user_sgpr_kernarg_preload_offset 0
		.amdhsa_user_sgpr_private_segment_size 0
		.amdhsa_uses_dynamic_stack 0
		.amdhsa_enable_private_segment 0
		.amdhsa_system_sgpr_workgroup_id_x 1
		.amdhsa_system_sgpr_workgroup_id_y 0
		.amdhsa_system_sgpr_workgroup_id_z 0
		.amdhsa_system_sgpr_workgroup_info 0
		.amdhsa_system_vgpr_workitem_id 0
		.amdhsa_next_free_vgpr 250
		.amdhsa_next_free_sgpr 102
		.amdhsa_accum_offset 252
		.amdhsa_reserve_vcc 1
		.amdhsa_float_round_mode_32 0
		.amdhsa_float_round_mode_16_64 0
		.amdhsa_float_denorm_mode_32 3
		.amdhsa_float_denorm_mode_16_64 3
		.amdhsa_dx10_clamp 1
		.amdhsa_ieee_mode 1
		.amdhsa_fp16_overflow 0
		.amdhsa_tg_split 0
		.amdhsa_exception_fp_ieee_invalid_op 0
		.amdhsa_exception_fp_denorm_src 0
		.amdhsa_exception_fp_ieee_div_zero 0
		.amdhsa_exception_fp_ieee_overflow 0
		.amdhsa_exception_fp_ieee_underflow 0
		.amdhsa_exception_fp_ieee_inexact 0
		.amdhsa_exception_int_div_zero 0
	.end_amdhsa_kernel

amdhsa.kernels:
  - .agpr_count:     0
    .args:
      - .offset:         0
        .size:           352
        .value_kind:     by_value
      - .offset:         352
        .size:           4
        .value_kind:     hidden_block_count_x
      - .offset:         356
        .size:           4
        .value_kind:     hidden_block_count_y
      - .offset:         360
        .size:           4
        .value_kind:     hidden_block_count_z
      - .offset:         364
        .size:           2
        .value_kind:     hidden_group_size_x
      - .offset:         366
        .size:           2
        .value_kind:     hidden_group_size_y
      - .offset:         368
        .size:           2
        .value_kind:     hidden_group_size_z
      - .offset:         370
        .size:           2
        .value_kind:     hidden_remainder_x
      - .offset:         372
        .size:           2
        .value_kind:     hidden_remainder_y
      - .offset:         374
        .size:           2
        .value_kind:     hidden_remainder_z
      - .offset:         392
        .size:           8
        .value_kind:     hidden_global_offset_x
      - .offset:         400
        .size:           8
        .value_kind:     hidden_global_offset_y
      - .offset:         408
        .size:           8
        .value_kind:     hidden_global_offset_z
      - .offset:         416
        .size:           2
        .value_kind:     hidden_grid_dims
      - .offset:         472
        .size:           4
        .value_kind:     hidden_dynamic_lds_size
    .group_segment_fixed_size: 0
    .kernarg_segment_align: 8
    .kernarg_segment_size: 608
    .language:       OpenCL C
    .language_version:
      - 2
      - 0
    .max_flat_workgroup_size: 512
    .name:           _Z10hybrid_fwd4Args
    .private_segment_fixed_size: 0
    .sgpr_count:     108
    .sgpr_spill_count: 171
    .symbol:         _Z10hybrid_fwd4Args.kd
    .uniform_work_group_size: 1
    .uses_dynamic_stack: false
    .vgpr_count:     250
    .vgpr_spill_count: 0
    .wavefront_size: 64
